# merge-GEMM phase: workgroups 128-255 (which own 2 instead of 3 tiles per GEMM) start about 12us late so their memory-bound epilogues interleave with the other half's MFMA main loops; on top of v7
# baseline (speedup 1.0000x reference)
.LBB0_864:
	s_cmpk_lt_u32 s2, 0x80
	s_cbranch_scc1 .Lstag_h_skip
	s_sleep 127
	s_sleep 127
	s_sleep 127
